# v108 plus DPP row rotations for the 16-lane sum of squares in the finalize-A row loop
# baseline (speedup 1.0000x reference)
; __device__ __forceinline__ float bf2f(bfu h) { return __uint_as_float(((unsigned)h) << 16); }
; __device__ __forceinline__ unsigned pack2(float a, float b) { return (unsigned)f2bf(a) | ((unsigned)f2bf(b) << 16); }
; __device__ __forceinline__ float frsq(float x) { return __builtin_amdgcn_rsqf(x); }
; __device__ __forceinline__ float siluf_(float x) { return x * frcp(1.0f + fexp(-x)); }
; #define SHX(v, m) shx_((v), (m), lane)
; __device__ void ab_fin_rows(const Params& p, int L, int row0, int nrows, const bool doA, const bool doB) {
;     ...
;   for (int rr = wid; rr < nrows; rr += 8) {
;     const long row = row0 + rr;
;     const int t = (int)(row & (TSEQ - 1));
;     bfu* pr = pab + row * 3584;
;     const int c0 = lane * 8;
;     if (doA) {
;     bf16x8 o = *(const bf16x8*)(pr + c0);
;     bf16x8 z = *(const bf16x8*)(pr + 1536 + c0);
;     float of[8]; float ss = 0.f;
;     for (int e = 0; e < 8; ++e) { of[e] = bf2f((bfu)o[e]); ss += of[e] * of[e]; }
;     ss += SHX(ss, 1); ss += SHX(ss, 2); ss += SHX(ss, 4); ss += SHX(ss, 8);
;     const float rs = frsq(ss * (1.0f / 128.0f) + 1e-6f);
;     float ra[8];
;     for (int e = 0; e < 8; ++e) ra[e] = of[e] * rs * p.dn_norm_g[li * 128 + ((c0 + e) & 127)] * siluf_(bf2f((bfu)z[e]));
;     uint4 wa; wa.x = pack2(ra[0], ra[1]); wa.y = pack2(ra[2], ra[3]); wa.z = pack2(ra[4], ra[5]); wa.w = pack2(ra[6], ra[7]);
;     *(uint4*)(pr + 512 + c0) = wa;
;     }
.LBB0_251:
	v_lshl_add_u64 v[68:69], v[20:21], 0, s[22:23]
	v_lshl_add_u64 v[70:71], v[68:69], 0, s[22:23]
	v_lshl_add_u64 v[72:73], v[70:71], 0, s[22:23]
	global_load_dwordx4 v[2:5], v[20:21], off
	global_load_dwordx4 v[14:17], v[20:21], off offset:3072
	global_load_dwordx4 v[10:13], v[18:19], off
	global_load_dwordx4 v[6:9], v[18:19], off offset:16
	global_load_dwordx4 v[52:55], v[68:69], off
	global_load_dwordx4 v[64:67], v[68:69], off offset:3072
	global_load_dwordx4 v[60:63], v[18:19], off
	global_load_dwordx4 v[56:59], v[18:19], off offset:16
	global_load_dwordx4 v[102:105], v[70:71], off
	global_load_dwordx4 v[114:117], v[70:71], off offset:3072
	global_load_dwordx4 v[110:113], v[18:19], off
	global_load_dwordx4 v[106:109], v[18:19], off offset:16
	global_load_dwordx4 v[152:155], v[72:73], off
	global_load_dwordx4 v[164:167], v[72:73], off offset:3072
	global_load_dwordx4 v[160:163], v[18:19], off
	global_load_dwordx4 v[156:159], v[18:19], off offset:16
	v_add_u32_e32 v0, 32, v0
	v_cmp_lt_i32_e32 vcc, s20, v0
	s_or_b64 s[12:13], vcc, s[12:13]
	s_waitcnt vmcnt(12)
	v_lshlrev_b32_e32 v27, 16, v3
	v_lshlrev_b32_e32 v26, 16, v2
	v_and_b32_e32 v3, 0xffff0000, v3
	v_and_b32_e32 v2, 0xffff0000, v2
	v_mov_b32_e32 v34, v6
	v_mov_b32_e32 v35, v8
	v_mov_b32_e32 v8, v7
	v_pk_mul_f32 v[6:7], v[26:27], v[26:27]
	v_pk_mul_f32 v[36:37], v[2:3], v[2:3]
	v_mov_b32_e32 v30, v10
	v_lshlrev_b32_e32 v10, 16, v4
	v_and_b32_e32 v4, 0xffff0000, v4
	v_add_f32_e32 v6, v6, v36
	v_mov_b32_e32 v38, v4
	v_mov_b32_e32 v39, v10
	v_add_f32_e32 v6, v7, v6
	v_mov_b32_e32 v31, v12
	v_mov_b32_e32 v12, v11
	v_lshlrev_b32_e32 v11, 16, v5
	v_and_b32_e32 v5, 0xffff0000, v5
	v_pk_mul_f32 v[38:39], v[38:39], v[38:39]
	v_add_f32_e32 v6, v37, v6
	v_mov_b32_e32 v40, v5
	v_mov_b32_e32 v41, v11
	v_add_f32_e32 v6, v39, v6
	v_pk_mul_f32 v[40:41], v[40:41], v[40:41]
	v_add_f32_e32 v6, v38, v6
	v_add_f32_e32 v6, v41, v6
	v_add_f32_e32 v6, v40, v6
	v_lshlrev_b32_e32 v29, 16, v15
	v_and_b32_e32 v15, 0xffff0000, v15
	v_mul_f32_e32 v45, 0xbfb8aa3b, v15
	v_exp_f32_e32 v45, v45
	s_waitcnt lgkmcnt(0)
	s_nop 1
	v_add_f32_dpp v36, v6, v6 row_ror:1 row_mask:0xf bank_mask:0xf
	v_lshlrev_b32_e32 v28, 16, v14
	v_lshlrev_b32_e32 v32, 16, v16
	v_add_f32_e32 v39, 1.0, v45
	v_mul_f32_e32 v42, 0xbfb8aa3b, v28
	s_waitcnt lgkmcnt(0)
	s_nop 1
	v_add_f32_dpp v41, v36, v36 row_ror:2 row_mask:0xf bank_mask:0xf
	v_mul_f32_e32 v44, 0xbfb8aa3b, v29
	v_mul_f32_e32 v46, 0xbfb8aa3b, v32
	v_exp_f32_e32 v42, v42
	v_exp_f32_e32 v44, v44
	v_exp_f32_e32 v46, v46
	s_waitcnt lgkmcnt(0)
	s_nop 1
	v_add_f32_dpp v45, v41, v41 row_ror:4 row_mask:0xf bank_mask:0xf
	v_add_f32_e32 v7, 1.0, v42
	v_add_f32_e32 v38, 1.0, v44
	v_add_f32_e32 v40, 1.0, v46
	v_and_b32_e32 v14, 0xffff0000, v14
	v_lshlrev_b32_e32 v33, 16, v17
	v_and_b32_e32 v17, 0xffff0000, v17
	v_and_b32_e32 v16, 0xffff0000, v16
	v_rcp_f32_e32 v6, v7
	v_rcp_f32_e32 v7, v38
	v_mul_f32_e32 v43, 0xbfb8aa3b, v14
	v_mul_f32_e32 v47, 0xbfb8aa3b, v16
	v_mul_f32_e32 v49, 0xbfb8aa3b, v17
	v_mul_f32_e32 v48, 0xbfb8aa3b, v33
	v_exp_f32_e32 v43, v43
	v_exp_f32_e32 v47, v47
	v_exp_f32_e32 v49, v49
	v_exp_f32_e32 v48, v48
	v_pk_mul_f32 v[6:7], v[6:7], v[28:29]
	s_waitcnt lgkmcnt(0)
	s_nop 1
	v_add_f32_dpp v28, v45, v45 row_ror:8 row_mask:0xf bank_mask:0xf
	v_fmamk_f32 v28, v28, 0x3c000000, v201
	v_add_f32_e32 v37, 1.0, v43
	v_add_f32_e32 v42, 1.0, v47
	v_add_f32_e32 v44, 1.0, v49
	v_rsq_f32_e32 v28, v28
	v_add_f32_e32 v43, 1.0, v48
	v_rcp_f32_e32 v36, v37
	v_rcp_f32_e32 v37, v39
	v_rcp_f32_e32 v38, v40
	v_rcp_f32_e32 v40, v42
	v_rcp_f32_e32 v41, v44
	v_rcp_f32_e32 v39, v43
	v_pk_mul_f32 v[2:3], v[28:29], v[2:3] op_sel_hi:[0,1]
	v_pk_mul_f32 v[4:5], v[28:29], v[4:5] op_sel_hi:[0,1]
	v_pk_mul_f32 v[14:15], v[36:37], v[14:15]
	v_pk_mul_f32 v[16:17], v[40:41], v[16:17]
	v_pk_mul_f32 v[26:27], v[28:29], v[26:27] op_sel_hi:[0,1]
	v_pk_mul_f32 v[10:11], v[28:29], v[10:11] op_sel_hi:[0,1]
	v_pk_mul_f32 v[2:3], v[12:13], v[2:3]
	v_pk_mul_f32 v[4:5], v[8:9], v[4:5]
	v_pk_mul_f32 v[32:33], v[38:39], v[32:33]
	v_pk_mul_f32 v[26:27], v[30:31], v[26:27]
	v_pk_mul_f32 v[10:11], v[34:35], v[10:11]
	v_pk_mul_f32 v[2:3], v[14:15], v[2:3]
	v_pk_mul_f32 v[4:5], v[16:17], v[4:5]
	v_pk_mul_f32 v[6:7], v[6:7], v[26:27]
	v_pk_mul_f32 v[8:9], v[32:33], v[10:11]
	v_and_b32_sdwa v12, v3, v220 dst_sel:DWORD dst_unused:UNUSED_PAD src0_sel:WORD_1 src1_sel:DWORD
	v_and_b32_sdwa v13, v2, v220 dst_sel:DWORD dst_unused:UNUSED_PAD src0_sel:WORD_1 src1_sel:DWORD
	v_and_b32_sdwa v16, v5, v220 dst_sel:DWORD dst_unused:UNUSED_PAD src0_sel:WORD_1 src1_sel:DWORD
	v_and_b32_sdwa v17, v4, v220 dst_sel:DWORD dst_unused:UNUSED_PAD src0_sel:WORD_1 src1_sel:DWORD
	v_and_b32_sdwa v10, v7, v220 dst_sel:DWORD dst_unused:UNUSED_PAD src0_sel:WORD_1 src1_sel:DWORD
	v_and_b32_sdwa v11, v6, v220 dst_sel:DWORD dst_unused:UNUSED_PAD src0_sel:WORD_1 src1_sel:DWORD
	v_and_b32_sdwa v14, v9, v220 dst_sel:DWORD dst_unused:UNUSED_PAD src0_sel:WORD_1 src1_sel:DWORD
	v_and_b32_sdwa v15, v8, v220 dst_sel:DWORD dst_unused:UNUSED_PAD src0_sel:WORD_1 src1_sel:DWORD
	v_add3_u32 v3, v3, v12, s72
	v_add3_u32 v2, v2, v13, s72
	v_add3_u32 v5, v5, v16, s72
	v_add3_u32 v4, v4, v17, s72
	v_add3_u32 v6, v6, v11, s72
	v_add3_u32 v7, v7, v10, s72
	v_add3_u32 v8, v8, v15, s72
	v_add3_u32 v9, v9, v14, s72
	v_and_b32_e32 v3, 0xffff0000, v3
	v_and_b32_e32 v2, 0xffff0000, v2
	v_and_b32_e32 v5, 0xffff0000, v5
	v_and_b32_e32 v4, 0xffff0000, v4
	v_or_b32_sdwa v3, v3, v7 dst_sel:DWORD dst_unused:UNUSED_PAD src0_sel:DWORD src1_sel:WORD_1
	v_or_b32_sdwa v2, v2, v6 dst_sel:DWORD dst_unused:UNUSED_PAD src0_sel:DWORD src1_sel:WORD_1
	v_or_b32_sdwa v5, v5, v9 dst_sel:DWORD dst_unused:UNUSED_PAD src0_sel:DWORD src1_sel:WORD_1
	v_or_b32_sdwa v4, v4, v8 dst_sel:DWORD dst_unused:UNUSED_PAD src0_sel:DWORD src1_sel:WORD_1
	global_store_dwordx4 v[20:21], v[2:5], off offset:1024
	s_waitcnt vmcnt(9)
; __device__ __forceinline__ float bf2f(bfu h) { return __uint_as_float(((unsigned)h) << 16); }
; __device__ __forceinline__ unsigned pack2(float a, float b) { return (unsigned)f2bf(a) | ((unsigned)f2bf(b) << 16); }
; __device__ __forceinline__ float frsq(float x) { return __builtin_amdgcn_rsqf(x); }
; __device__ __forceinline__ float siluf_(float x) { return x * frcp(1.0f + fexp(-x)); }
; #define SHX(v, m) shx_((v), (m), lane)
; __device__ void ab_fin_rows(const Params& p, int L, int row0, int nrows, const bool doA, const bool doB) {
;     ...
;     if (doA) {
;     bf16x8 o = *(const bf16x8*)(pr + c0);
;     bf16x8 z = *(const bf16x8*)(pr + 1536 + c0);
;     float of[8]; float ss = 0.f;
;     for (int e = 0; e < 8; ++e) { of[e] = bf2f((bfu)o[e]); ss += of[e] * of[e]; }
;     ss += SHX(ss, 1); ss += SHX(ss, 2); ss += SHX(ss, 4); ss += SHX(ss, 8);
;     const float rs = frsq(ss * (1.0f / 128.0f) + 1e-6f);
;     float ra[8];
;     for (int e = 0; e < 8; ++e) ra[e] = of[e] * rs * p.dn_norm_g[li * 128 + ((c0 + e) & 127)] * siluf_(bf2f((bfu)z[e]));
;     uint4 wa; wa.x = pack2(ra[0], ra[1]); wa.y = pack2(ra[2], ra[3]); wa.z = pack2(ra[4], ra[5]); wa.w = pack2(ra[6], ra[7]);
;     *(uint4*)(pr + 512 + c0) = wa;
;     }
	v_lshlrev_b32_e32 v77, 16, v53
	v_lshlrev_b32_e32 v76, 16, v52
	v_and_b32_e32 v53, 0xffff0000, v53
	v_and_b32_e32 v52, 0xffff0000, v52
	v_mov_b32_e32 v84, v56
	v_mov_b32_e32 v85, v58
	v_mov_b32_e32 v58, v57
	v_pk_mul_f32 v[56:57], v[76:77], v[76:77]
	v_pk_mul_f32 v[86:87], v[52:53], v[52:53]
	v_mov_b32_e32 v80, v60
	v_lshlrev_b32_e32 v60, 16, v54
	v_and_b32_e32 v54, 0xffff0000, v54
	v_add_f32_e32 v56, v56, v86
	v_mov_b32_e32 v88, v54
	v_mov_b32_e32 v89, v60
	v_add_f32_e32 v56, v57, v56
	v_mov_b32_e32 v81, v62
	v_mov_b32_e32 v62, v61
	v_lshlrev_b32_e32 v61, 16, v55
	v_and_b32_e32 v55, 0xffff0000, v55
	v_pk_mul_f32 v[88:89], v[88:89], v[88:89]
	v_add_f32_e32 v56, v87, v56
	v_mov_b32_e32 v90, v55
	v_mov_b32_e32 v91, v61
	v_add_f32_e32 v56, v89, v56
	v_pk_mul_f32 v[90:91], v[90:91], v[90:91]
	v_add_f32_e32 v56, v88, v56
	v_add_f32_e32 v56, v91, v56
	v_add_f32_e32 v56, v90, v56
	v_lshlrev_b32_e32 v79, 16, v65
	v_and_b32_e32 v65, 0xffff0000, v65
	v_mul_f32_e32 v95, 0xbfb8aa3b, v65
	v_exp_f32_e32 v95, v95
	s_waitcnt lgkmcnt(0)
	s_nop 1
	v_add_f32_dpp v86, v56, v56 row_ror:1 row_mask:0xf bank_mask:0xf
	v_lshlrev_b32_e32 v78, 16, v64
	v_lshlrev_b32_e32 v82, 16, v66
	v_add_f32_e32 v89, 1.0, v95
	v_mul_f32_e32 v92, 0xbfb8aa3b, v78
	s_waitcnt lgkmcnt(0)
	s_nop 1
	v_add_f32_dpp v91, v86, v86 row_ror:2 row_mask:0xf bank_mask:0xf
	v_mul_f32_e32 v94, 0xbfb8aa3b, v79
	v_mul_f32_e32 v96, 0xbfb8aa3b, v82
	v_exp_f32_e32 v92, v92
	v_exp_f32_e32 v94, v94
	v_exp_f32_e32 v96, v96
	s_waitcnt lgkmcnt(0)
	s_nop 1
	v_add_f32_dpp v95, v91, v91 row_ror:4 row_mask:0xf bank_mask:0xf
	v_add_f32_e32 v57, 1.0, v92
	v_add_f32_e32 v88, 1.0, v94
	v_add_f32_e32 v90, 1.0, v96
	v_and_b32_e32 v64, 0xffff0000, v64
	v_lshlrev_b32_e32 v83, 16, v67
	v_and_b32_e32 v67, 0xffff0000, v67
	v_and_b32_e32 v66, 0xffff0000, v66
	v_rcp_f32_e32 v56, v57
	v_rcp_f32_e32 v57, v88
	v_mul_f32_e32 v93, 0xbfb8aa3b, v64
	v_mul_f32_e32 v97, 0xbfb8aa3b, v66
	v_mul_f32_e32 v99, 0xbfb8aa3b, v67
	v_mul_f32_e32 v98, 0xbfb8aa3b, v83
	v_exp_f32_e32 v93, v93
	v_exp_f32_e32 v97, v97
	v_exp_f32_e32 v99, v99
	v_exp_f32_e32 v98, v98
	v_pk_mul_f32 v[56:57], v[56:57], v[78:79]
	s_waitcnt lgkmcnt(0)
	s_nop 1
	v_add_f32_dpp v78, v95, v95 row_ror:8 row_mask:0xf bank_mask:0xf
	v_fmamk_f32 v78, v78, 0x3c000000, v201
	v_add_f32_e32 v87, 1.0, v93
	v_add_f32_e32 v92, 1.0, v97
	v_add_f32_e32 v94, 1.0, v99
	v_rsq_f32_e32 v78, v78
	v_add_f32_e32 v93, 1.0, v98
	v_rcp_f32_e32 v86, v87
	v_rcp_f32_e32 v87, v89
	v_rcp_f32_e32 v88, v90
	v_rcp_f32_e32 v90, v92
	v_rcp_f32_e32 v91, v94
	v_rcp_f32_e32 v89, v93
	v_pk_mul_f32 v[52:53], v[78:79], v[52:53] op_sel_hi:[0,1]
	v_pk_mul_f32 v[54:55], v[78:79], v[54:55] op_sel_hi:[0,1]
	v_pk_mul_f32 v[64:65], v[86:87], v[64:65]
	v_pk_mul_f32 v[66:67], v[90:91], v[66:67]
	v_pk_mul_f32 v[76:77], v[78:79], v[76:77] op_sel_hi:[0,1]
	v_pk_mul_f32 v[60:61], v[78:79], v[60:61] op_sel_hi:[0,1]
	v_pk_mul_f32 v[52:53], v[62:63], v[52:53]
	v_pk_mul_f32 v[54:55], v[58:59], v[54:55]
	v_pk_mul_f32 v[82:83], v[88:89], v[82:83]
	v_pk_mul_f32 v[76:77], v[80:81], v[76:77]
	v_pk_mul_f32 v[60:61], v[84:85], v[60:61]
	v_pk_mul_f32 v[52:53], v[64:65], v[52:53]
	v_pk_mul_f32 v[54:55], v[66:67], v[54:55]
	v_pk_mul_f32 v[56:57], v[56:57], v[76:77]
	v_pk_mul_f32 v[58:59], v[82:83], v[60:61]
	v_and_b32_sdwa v62, v53, v220 dst_sel:DWORD dst_unused:UNUSED_PAD src0_sel:WORD_1 src1_sel:DWORD
	v_and_b32_sdwa v63, v52, v220 dst_sel:DWORD dst_unused:UNUSED_PAD src0_sel:WORD_1 src1_sel:DWORD
	v_and_b32_sdwa v66, v55, v220 dst_sel:DWORD dst_unused:UNUSED_PAD src0_sel:WORD_1 src1_sel:DWORD
	v_and_b32_sdwa v67, v54, v220 dst_sel:DWORD dst_unused:UNUSED_PAD src0_sel:WORD_1 src1_sel:DWORD
	v_and_b32_sdwa v60, v57, v220 dst_sel:DWORD dst_unused:UNUSED_PAD src0_sel:WORD_1 src1_sel:DWORD
	v_and_b32_sdwa v61, v56, v220 dst_sel:DWORD dst_unused:UNUSED_PAD src0_sel:WORD_1 src1_sel:DWORD
	v_and_b32_sdwa v64, v59, v220 dst_sel:DWORD dst_unused:UNUSED_PAD src0_sel:WORD_1 src1_sel:DWORD
	v_and_b32_sdwa v65, v58, v220 dst_sel:DWORD dst_unused:UNUSED_PAD src0_sel:WORD_1 src1_sel:DWORD
	v_add3_u32 v53, v53, v62, s72
	v_add3_u32 v52, v52, v63, s72
	v_add3_u32 v55, v55, v66, s72
	v_add3_u32 v54, v54, v67, s72
	v_add3_u32 v56, v56, v61, s72
	v_add3_u32 v57, v57, v60, s72
	v_add3_u32 v58, v58, v65, s72
	v_add3_u32 v59, v59, v64, s72
	v_and_b32_e32 v53, 0xffff0000, v53
	v_and_b32_e32 v52, 0xffff0000, v52
	v_and_b32_e32 v55, 0xffff0000, v55
	v_and_b32_e32 v54, 0xffff0000, v54
	v_or_b32_sdwa v53, v53, v57 dst_sel:DWORD dst_unused:UNUSED_PAD src0_sel:DWORD src1_sel:WORD_1
	v_or_b32_sdwa v52, v52, v56 dst_sel:DWORD dst_unused:UNUSED_PAD src0_sel:DWORD src1_sel:WORD_1
	v_or_b32_sdwa v55, v55, v59 dst_sel:DWORD dst_unused:UNUSED_PAD src0_sel:DWORD src1_sel:WORD_1
	v_or_b32_sdwa v54, v54, v58 dst_sel:DWORD dst_unused:UNUSED_PAD src0_sel:DWORD src1_sel:WORD_1
	global_store_dwordx4 v[68:69], v[52:55], off offset:1024
	s_waitcnt vmcnt(6)
	v_lshlrev_b32_e32 v127, 16, v103
	v_lshlrev_b32_e32 v126, 16, v102
	v_and_b32_e32 v103, 0xffff0000, v103
	v_and_b32_e32 v102, 0xffff0000, v102
	v_mov_b32_e32 v134, v106
	v_mov_b32_e32 v135, v108
	v_mov_b32_e32 v108, v107
	v_pk_mul_f32 v[106:107], v[126:127], v[126:127]
	v_pk_mul_f32 v[136:137], v[102:103], v[102:103]
	v_mov_b32_e32 v130, v110
	v_lshlrev_b32_e32 v110, 16, v104
	v_and_b32_e32 v104, 0xffff0000, v104
	v_add_f32_e32 v106, v106, v136
	v_mov_b32_e32 v138, v104
	v_mov_b32_e32 v139, v110
	v_add_f32_e32 v106, v107, v106
	v_mov_b32_e32 v131, v112
	v_mov_b32_e32 v112, v111
	v_lshlrev_b32_e32 v111, 16, v105
	v_and_b32_e32 v105, 0xffff0000, v105
	v_pk_mul_f32 v[138:139], v[138:139], v[138:139]
	v_add_f32_e32 v106, v137, v106
	v_mov_b32_e32 v140, v105
	v_mov_b32_e32 v141, v111
	v_add_f32_e32 v106, v139, v106
	v_pk_mul_f32 v[140:141], v[140:141], v[140:141]
	v_add_f32_e32 v106, v138, v106
	v_add_f32_e32 v106, v141, v106
	v_add_f32_e32 v106, v140, v106
	v_lshlrev_b32_e32 v129, 16, v115
	v_and_b32_e32 v115, 0xffff0000, v115
	v_mul_f32_e32 v145, 0xbfb8aa3b, v115
	v_exp_f32_e32 v145, v145
	s_waitcnt lgkmcnt(0)
; __device__ __forceinline__ float bf2f(bfu h) { return __uint_as_float(((unsigned)h) << 16); }
; __device__ __forceinline__ unsigned pack2(float a, float b) { return (unsigned)f2bf(a) | ((unsigned)f2bf(b) << 16); }
; __device__ __forceinline__ float frsq(float x) { return __builtin_amdgcn_rsqf(x); }
; __device__ __forceinline__ float siluf_(float x) { return x * frcp(1.0f + fexp(-x)); }
; #define SHX(v, m) shx_((v), (m), lane)
; __device__ void ab_fin_rows(const Params& p, int L, int row0, int nrows, const bool doA, const bool doB) {
;     ...
;     if (doA) {
;     bf16x8 o = *(const bf16x8*)(pr + c0);
;     bf16x8 z = *(const bf16x8*)(pr + 1536 + c0);
;     float of[8]; float ss = 0.f;
;     for (int e = 0; e < 8; ++e) { of[e] = bf2f((bfu)o[e]); ss += of[e] * of[e]; }
;     ss += SHX(ss, 1); ss += SHX(ss, 2); ss += SHX(ss, 4); ss += SHX(ss, 8);
;     const float rs = frsq(ss * (1.0f / 128.0f) + 1e-6f);
;     float ra[8];
;     for (int e = 0; e < 8; ++e) ra[e] = of[e] * rs * p.dn_norm_g[li * 128 + ((c0 + e) & 127)] * siluf_(bf2f((bfu)z[e]));
;     uint4 wa; wa.x = pack2(ra[0], ra[1]); wa.y = pack2(ra[2], ra[3]); wa.z = pack2(ra[4], ra[5]); wa.w = pack2(ra[6], ra[7]);
;     *(uint4*)(pr + 512 + c0) = wa;
;     }
	s_nop 1
	v_add_f32_dpp v136, v106, v106 row_ror:1 row_mask:0xf bank_mask:0xf
	v_lshlrev_b32_e32 v128, 16, v114
	v_lshlrev_b32_e32 v132, 16, v116
	v_add_f32_e32 v139, 1.0, v145
	v_mul_f32_e32 v142, 0xbfb8aa3b, v128
	s_waitcnt lgkmcnt(0)
	s_nop 1
	v_add_f32_dpp v141, v136, v136 row_ror:2 row_mask:0xf bank_mask:0xf
	v_mul_f32_e32 v144, 0xbfb8aa3b, v129
	v_mul_f32_e32 v146, 0xbfb8aa3b, v132
	v_exp_f32_e32 v142, v142
	v_exp_f32_e32 v144, v144
	v_exp_f32_e32 v146, v146
	s_waitcnt lgkmcnt(0)
	s_nop 1
	v_add_f32_dpp v145, v141, v141 row_ror:4 row_mask:0xf bank_mask:0xf
	v_add_f32_e32 v107, 1.0, v142
	v_add_f32_e32 v138, 1.0, v144
	v_add_f32_e32 v140, 1.0, v146
	v_and_b32_e32 v114, 0xffff0000, v114
	v_lshlrev_b32_e32 v133, 16, v117
	v_and_b32_e32 v117, 0xffff0000, v117
	v_and_b32_e32 v116, 0xffff0000, v116
	v_rcp_f32_e32 v106, v107
	v_rcp_f32_e32 v107, v138
	v_mul_f32_e32 v143, 0xbfb8aa3b, v114
	v_mul_f32_e32 v147, 0xbfb8aa3b, v116
	v_mul_f32_e32 v149, 0xbfb8aa3b, v117
	v_mul_f32_e32 v148, 0xbfb8aa3b, v133
	v_exp_f32_e32 v143, v143
	v_exp_f32_e32 v147, v147
	v_exp_f32_e32 v149, v149
	v_exp_f32_e32 v148, v148
	v_pk_mul_f32 v[106:107], v[106:107], v[128:129]
	s_waitcnt lgkmcnt(0)
	s_nop 1
	v_add_f32_dpp v128, v145, v145 row_ror:8 row_mask:0xf bank_mask:0xf
	v_fmamk_f32 v128, v128, 0x3c000000, v201
	v_add_f32_e32 v137, 1.0, v143
	v_add_f32_e32 v142, 1.0, v147
	v_add_f32_e32 v144, 1.0, v149
	v_rsq_f32_e32 v128, v128
	v_add_f32_e32 v143, 1.0, v148
	v_rcp_f32_e32 v136, v137
	v_rcp_f32_e32 v137, v139
	v_rcp_f32_e32 v138, v140
	v_rcp_f32_e32 v140, v142
	v_rcp_f32_e32 v141, v144
	v_rcp_f32_e32 v139, v143
	v_pk_mul_f32 v[102:103], v[128:129], v[102:103] op_sel_hi:[0,1]
	v_pk_mul_f32 v[104:105], v[128:129], v[104:105] op_sel_hi:[0,1]
	v_pk_mul_f32 v[114:115], v[136:137], v[114:115]
	v_pk_mul_f32 v[116:117], v[140:141], v[116:117]
	v_pk_mul_f32 v[126:127], v[128:129], v[126:127] op_sel_hi:[0,1]
	v_pk_mul_f32 v[110:111], v[128:129], v[110:111] op_sel_hi:[0,1]
	v_pk_mul_f32 v[102:103], v[112:113], v[102:103]
	v_pk_mul_f32 v[104:105], v[108:109], v[104:105]
	v_pk_mul_f32 v[132:133], v[138:139], v[132:133]
	v_pk_mul_f32 v[126:127], v[130:131], v[126:127]
	v_pk_mul_f32 v[110:111], v[134:135], v[110:111]
	v_pk_mul_f32 v[102:103], v[114:115], v[102:103]
	v_pk_mul_f32 v[104:105], v[116:117], v[104:105]
	v_pk_mul_f32 v[106:107], v[106:107], v[126:127]
	v_pk_mul_f32 v[108:109], v[132:133], v[110:111]
	v_and_b32_sdwa v112, v103, v220 dst_sel:DWORD dst_unused:UNUSED_PAD src0_sel:WORD_1 src1_sel:DWORD
	v_and_b32_sdwa v113, v102, v220 dst_sel:DWORD dst_unused:UNUSED_PAD src0_sel:WORD_1 src1_sel:DWORD
	v_and_b32_sdwa v116, v105, v220 dst_sel:DWORD dst_unused:UNUSED_PAD src0_sel:WORD_1 src1_sel:DWORD
	v_and_b32_sdwa v117, v104, v220 dst_sel:DWORD dst_unused:UNUSED_PAD src0_sel:WORD_1 src1_sel:DWORD
	v_and_b32_sdwa v110, v107, v220 dst_sel:DWORD dst_unused:UNUSED_PAD src0_sel:WORD_1 src1_sel:DWORD
	v_and_b32_sdwa v111, v106, v220 dst_sel:DWORD dst_unused:UNUSED_PAD src0_sel:WORD_1 src1_sel:DWORD
	v_and_b32_sdwa v114, v109, v220 dst_sel:DWORD dst_unused:UNUSED_PAD src0_sel:WORD_1 src1_sel:DWORD
	v_and_b32_sdwa v115, v108, v220 dst_sel:DWORD dst_unused:UNUSED_PAD src0_sel:WORD_1 src1_sel:DWORD
	v_add3_u32 v103, v103, v112, s72
	v_add3_u32 v102, v102, v113, s72
	v_add3_u32 v105, v105, v116, s72
	v_add3_u32 v104, v104, v117, s72
	v_add3_u32 v106, v106, v111, s72
	v_add3_u32 v107, v107, v110, s72
	v_add3_u32 v108, v108, v115, s72
	v_add3_u32 v109, v109, v114, s72
	v_and_b32_e32 v103, 0xffff0000, v103
	v_and_b32_e32 v102, 0xffff0000, v102
	v_and_b32_e32 v105, 0xffff0000, v105
	v_and_b32_e32 v104, 0xffff0000, v104
	v_or_b32_sdwa v103, v103, v107 dst_sel:DWORD dst_unused:UNUSED_PAD src0_sel:DWORD src1_sel:WORD_1
	v_or_b32_sdwa v102, v102, v106 dst_sel:DWORD dst_unused:UNUSED_PAD src0_sel:DWORD src1_sel:WORD_1
	v_or_b32_sdwa v105, v105, v109 dst_sel:DWORD dst_unused:UNUSED_PAD src0_sel:DWORD src1_sel:WORD_1
	v_or_b32_sdwa v104, v104, v108 dst_sel:DWORD dst_unused:UNUSED_PAD src0_sel:DWORD src1_sel:WORD_1
	global_store_dwordx4 v[70:71], v[102:105], off offset:1024
	s_waitcnt vmcnt(3)
	v_lshlrev_b32_e32 v177, 16, v153
	v_lshlrev_b32_e32 v176, 16, v152
	v_and_b32_e32 v153, 0xffff0000, v153
	v_and_b32_e32 v152, 0xffff0000, v152
	v_mov_b32_e32 v184, v156
	v_mov_b32_e32 v185, v158
	v_mov_b32_e32 v158, v157
	v_pk_mul_f32 v[156:157], v[176:177], v[176:177]
	v_pk_mul_f32 v[186:187], v[152:153], v[152:153]
	v_mov_b32_e32 v180, v160
	v_lshlrev_b32_e32 v160, 16, v154
	v_and_b32_e32 v154, 0xffff0000, v154
	v_add_f32_e32 v156, v156, v186
	v_mov_b32_e32 v188, v154
	v_mov_b32_e32 v189, v160
	v_add_f32_e32 v156, v157, v156
	v_mov_b32_e32 v181, v162
	v_mov_b32_e32 v162, v161
	v_lshlrev_b32_e32 v161, 16, v155
	v_and_b32_e32 v155, 0xffff0000, v155
	v_pk_mul_f32 v[188:189], v[188:189], v[188:189]
	v_add_f32_e32 v156, v187, v156
	v_mov_b32_e32 v190, v155
	v_mov_b32_e32 v191, v161
	v_add_f32_e32 v156, v189, v156
	v_pk_mul_f32 v[190:191], v[190:191], v[190:191]
	v_add_f32_e32 v156, v188, v156
	v_add_f32_e32 v156, v191, v156
	v_add_f32_e32 v156, v190, v156
	v_lshlrev_b32_e32 v179, 16, v165
	v_and_b32_e32 v165, 0xffff0000, v165
	v_mul_f32_e32 v195, 0xbfb8aa3b, v165
	v_exp_f32_e32 v195, v195
	s_waitcnt lgkmcnt(0)
; __device__ __forceinline__ float bf2f(bfu h) { return __uint_as_float(((unsigned)h) << 16); }
; __device__ __forceinline__ unsigned pack2(float a, float b) { return (unsigned)f2bf(a) | ((unsigned)f2bf(b) << 16); }
; __device__ __forceinline__ float frsq(float x) { return __builtin_amdgcn_rsqf(x); }
; __device__ __forceinline__ float siluf_(float x) { return x * frcp(1.0f + fexp(-x)); }
; #define SHX(v, m) shx_((v), (m), lane)
; __device__ void ab_fin_rows(const Params& p, int L, int row0, int nrows, const bool doA, const bool doB) {
;     ...
;   for (int rr = wid; rr < nrows; rr += 8) {
;     const long row = row0 + rr;
;     const int t = (int)(row & (TSEQ - 1));
;     bfu* pr = pab + row * 3584;
;     const int c0 = lane * 8;
;     if (doA) {
;     bf16x8 o = *(const bf16x8*)(pr + c0);
;     bf16x8 z = *(const bf16x8*)(pr + 1536 + c0);
;     float of[8]; float ss = 0.f;
;     for (int e = 0; e < 8; ++e) { of[e] = bf2f((bfu)o[e]); ss += of[e] * of[e]; }
;     ss += SHX(ss, 1); ss += SHX(ss, 2); ss += SHX(ss, 4); ss += SHX(ss, 8);
;     const float rs = frsq(ss * (1.0f / 128.0f) + 1e-6f);
;     float ra[8];
;     for (int e = 0; e < 8; ++e) ra[e] = of[e] * rs * p.dn_norm_g[li * 128 + ((c0 + e) & 127)] * siluf_(bf2f((bfu)z[e]));
;     uint4 wa; wa.x = pack2(ra[0], ra[1]); wa.y = pack2(ra[2], ra[3]); wa.z = pack2(ra[4], ra[5]); wa.w = pack2(ra[6], ra[7]);
;     *(uint4*)(pr + 512 + c0) = wa;
;     }
	s_nop 1
	v_add_f32_dpp v186, v156, v156 row_ror:1 row_mask:0xf bank_mask:0xf
	v_lshlrev_b32_e32 v178, 16, v164
	v_lshlrev_b32_e32 v182, 16, v166
	v_add_f32_e32 v189, 1.0, v195
	v_mul_f32_e32 v192, 0xbfb8aa3b, v178
	s_waitcnt lgkmcnt(0)
	s_nop 1
	v_add_f32_dpp v191, v186, v186 row_ror:2 row_mask:0xf bank_mask:0xf
	v_mul_f32_e32 v194, 0xbfb8aa3b, v179
	v_mul_f32_e32 v196, 0xbfb8aa3b, v182
	v_exp_f32_e32 v192, v192
	v_exp_f32_e32 v194, v194
	v_exp_f32_e32 v196, v196
	s_waitcnt lgkmcnt(0)
	s_nop 1
	v_add_f32_dpp v195, v191, v191 row_ror:4 row_mask:0xf bank_mask:0xf
	v_add_f32_e32 v157, 1.0, v192
	v_add_f32_e32 v188, 1.0, v194
	v_add_f32_e32 v190, 1.0, v196
	v_and_b32_e32 v164, 0xffff0000, v164
	v_lshlrev_b32_e32 v183, 16, v167
	v_and_b32_e32 v167, 0xffff0000, v167
	v_and_b32_e32 v166, 0xffff0000, v166
	v_rcp_f32_e32 v156, v157
	v_rcp_f32_e32 v157, v188
	v_mul_f32_e32 v193, 0xbfb8aa3b, v164
	v_mul_f32_e32 v197, 0xbfb8aa3b, v166
	v_mul_f32_e32 v199, 0xbfb8aa3b, v167
	v_mul_f32_e32 v198, 0xbfb8aa3b, v183
	v_exp_f32_e32 v193, v193
	v_exp_f32_e32 v197, v197
	v_exp_f32_e32 v199, v199
	v_exp_f32_e32 v198, v198
	v_pk_mul_f32 v[156:157], v[156:157], v[178:179]
	s_waitcnt lgkmcnt(0)
	s_nop 1
	v_add_f32_dpp v178, v195, v195 row_ror:8 row_mask:0xf bank_mask:0xf
	v_fmamk_f32 v178, v178, 0x3c000000, v201
	v_add_f32_e32 v187, 1.0, v193
	v_add_f32_e32 v192, 1.0, v197
	v_add_f32_e32 v194, 1.0, v199
	v_rsq_f32_e32 v178, v178
	v_add_f32_e32 v193, 1.0, v198
	v_rcp_f32_e32 v186, v187
	v_rcp_f32_e32 v187, v189
	v_rcp_f32_e32 v188, v190
	v_rcp_f32_e32 v190, v192
	v_rcp_f32_e32 v191, v194
	v_rcp_f32_e32 v189, v193
	v_pk_mul_f32 v[152:153], v[178:179], v[152:153] op_sel_hi:[0,1]
	v_pk_mul_f32 v[154:155], v[178:179], v[154:155] op_sel_hi:[0,1]
	v_pk_mul_f32 v[164:165], v[186:187], v[164:165]
	v_pk_mul_f32 v[166:167], v[190:191], v[166:167]
	v_pk_mul_f32 v[176:177], v[178:179], v[176:177] op_sel_hi:[0,1]
	v_pk_mul_f32 v[160:161], v[178:179], v[160:161] op_sel_hi:[0,1]
	v_pk_mul_f32 v[152:153], v[162:163], v[152:153]
	v_pk_mul_f32 v[154:155], v[158:159], v[154:155]
	v_pk_mul_f32 v[182:183], v[188:189], v[182:183]
	v_pk_mul_f32 v[176:177], v[180:181], v[176:177]
	v_pk_mul_f32 v[160:161], v[184:185], v[160:161]
	v_pk_mul_f32 v[152:153], v[164:165], v[152:153]
	v_pk_mul_f32 v[154:155], v[166:167], v[154:155]
	v_pk_mul_f32 v[156:157], v[156:157], v[176:177]
	v_pk_mul_f32 v[158:159], v[182:183], v[160:161]
	v_and_b32_sdwa v162, v153, v220 dst_sel:DWORD dst_unused:UNUSED_PAD src0_sel:WORD_1 src1_sel:DWORD
	v_and_b32_sdwa v163, v152, v220 dst_sel:DWORD dst_unused:UNUSED_PAD src0_sel:WORD_1 src1_sel:DWORD
	v_and_b32_sdwa v166, v155, v220 dst_sel:DWORD dst_unused:UNUSED_PAD src0_sel:WORD_1 src1_sel:DWORD
	v_and_b32_sdwa v167, v154, v220 dst_sel:DWORD dst_unused:UNUSED_PAD src0_sel:WORD_1 src1_sel:DWORD
	v_and_b32_sdwa v160, v157, v220 dst_sel:DWORD dst_unused:UNUSED_PAD src0_sel:WORD_1 src1_sel:DWORD
	v_and_b32_sdwa v161, v156, v220 dst_sel:DWORD dst_unused:UNUSED_PAD src0_sel:WORD_1 src1_sel:DWORD
	v_and_b32_sdwa v164, v159, v220 dst_sel:DWORD dst_unused:UNUSED_PAD src0_sel:WORD_1 src1_sel:DWORD
	v_and_b32_sdwa v165, v158, v220 dst_sel:DWORD dst_unused:UNUSED_PAD src0_sel:WORD_1 src1_sel:DWORD
	v_add3_u32 v153, v153, v162, s72
	v_add3_u32 v152, v152, v163, s72
	v_add3_u32 v155, v155, v166, s72
	v_add3_u32 v154, v154, v167, s72
	v_add3_u32 v156, v156, v161, s72
	v_add3_u32 v157, v157, v160, s72
	v_add3_u32 v158, v158, v165, s72
	v_add3_u32 v159, v159, v164, s72
	v_and_b32_e32 v153, 0xffff0000, v153
	v_and_b32_e32 v152, 0xffff0000, v152
	v_and_b32_e32 v155, 0xffff0000, v155
	v_and_b32_e32 v154, 0xffff0000, v154
	v_or_b32_sdwa v153, v153, v157 dst_sel:DWORD dst_unused:UNUSED_PAD src0_sel:DWORD src1_sel:WORD_1
	v_or_b32_sdwa v152, v152, v156 dst_sel:DWORD dst_unused:UNUSED_PAD src0_sel:DWORD src1_sel:WORD_1
	v_or_b32_sdwa v155, v155, v159 dst_sel:DWORD dst_unused:UNUSED_PAD src0_sel:DWORD src1_sel:WORD_1
	v_or_b32_sdwa v154, v154, v158 dst_sel:DWORD dst_unused:UNUSED_PAD src0_sel:DWORD src1_sel:WORD_1
	global_store_dwordx4 v[72:73], v[152:155], off offset:1024
	v_lshl_add_u64 v[20:21], v[72:73], 0, s[22:23]
	s_andn2_b64 exec, exec, s[12:13]
	s_cbranch_execnz .LBB0_251
	s_branch .LBB0_248
